# attention unit epilogue: 15 gain-vector loads issued together (global loads into free registers) instead of one per vmcnt(0) lgkmcnt(0)
# speedup vs baseline: 1.0001x; 1.0001x over previous
.LBB0_420:
	s_andn2_b64 vcc, exec, s[62:63]
	s_waitcnt vmcnt(0) lgkmcnt(0)
	s_barrier
	s_cbranch_vccnz .LBB0_400
	ds_read_b128 v[104:107], v215
	ds_read_b128 v[108:111], v215 offset:32
	ds_read_b128 v[112:115], v215 offset:64
	ds_read_b128 v[116:119], v215 offset:96
	ds_read_b128 v[120:123], v215 offset:128
	ds_read_b128 v[124:127], v215 offset:160
	ds_read_b128 v[128:131], v215 offset:192
	ds_read_b128 v[132:135], v215 offset:224
	ds_read_b128 v[136:139], v215 offset:256
	ds_read_b128 v[140:143], v215 offset:288
	ds_read_b128 v[144:147], v215 offset:448
	ds_read_b128 v[148:151], v215 offset:320
	ds_read_b128 v[152:155], v215 offset:352
	ds_read_b128 v[156:159], v215 offset:480
	ds_read_b128 v[216:219], v215 offset:384
	ds_read_b128 v[220:223], v215 offset:416
	s_waitcnt lgkmcnt(14)
	v_pk_mul_f32 v[104:105], v[170:171], v[104:105]
	s_waitcnt lgkmcnt(5)
	v_pk_mul_f32 v[98:99], v[170:171], v[146:147]
	v_pk_fma_f32 v[104:105], v[48:49], v[96:97], v[104:105] op_sel_hi:[1,0,1] neg_lo:[0,0,1] neg_hi:[0,0,1]
	v_pk_mul_f32 v[48:49], v[170:171], v[106:107]
	v_pk_fma_f32 v[100:101], v[10:11], v[96:97], v[98:99] op_sel_hi:[1,0,1] neg_lo:[0,0,1] neg_hi:[0,0,1]
	v_pk_fma_f32 v[106:107], v[50:51], v[96:97], v[48:49] op_sel_hi:[1,0,1] neg_lo:[0,0,1] neg_hi:[0,0,1]
	v_pk_mul_f32 v[48:49], v[170:171], v[108:109]
	v_pk_mul_f32 v[50:51], v[170:171], v[110:111]
	v_pk_fma_f32 v[48:49], v[52:53], v[96:97], v[48:49] op_sel_hi:[1,0,1] neg_lo:[0,0,1] neg_hi:[0,0,1]
	v_pk_mul_f32 v[52:53], v[170:171], v[114:115]
	v_pk_fma_f32 v[108:109], v[54:55], v[96:97], v[50:51] op_sel_hi:[1,0,1] neg_lo:[0,0,1] neg_hi:[0,0,1]
	v_pk_fma_f32 v[110:111], v[58:59], v[96:97], v[52:53] op_sel_hi:[1,0,1] neg_lo:[0,0,1] neg_hi:[0,0,1]
	v_pk_mul_f32 v[52:53], v[170:171], v[116:117]
	v_pk_mul_f32 v[54:55], v[170:171], v[118:119]
	v_pk_fma_f32 v[52:53], v[60:61], v[96:97], v[52:53] op_sel_hi:[1,0,1] neg_lo:[0,0,1] neg_hi:[0,0,1]
	v_pk_fma_f32 v[60:61], v[62:63], v[96:97], v[54:55] op_sel_hi:[1,0,1] neg_lo:[0,0,1] neg_hi:[0,0,1]
	v_pk_mul_f32 v[54:55], v[170:171], v[120:121]
	v_pk_mul_f32 v[50:51], v[170:171], v[112:113]
	v_pk_fma_f32 v[32:33], v[32:33], v[96:97], v[54:55] op_sel_hi:[1,0,1] neg_lo:[0,0,1] neg_hi:[0,0,1]
	v_pk_mul_f32 v[54:55], v[170:171], v[122:123]
	v_pk_fma_f32 v[50:51], v[56:57], v[96:97], v[50:51] op_sel_hi:[1,0,1] neg_lo:[0,0,1] neg_hi:[0,0,1]
	v_pk_fma_f32 v[54:55], v[34:35], v[96:97], v[54:55] op_sel_hi:[1,0,1] neg_lo:[0,0,1] neg_hi:[0,0,1]
	v_pk_mul_f32 v[34:35], v[170:171], v[124:125]
	s_waitcnt lgkmcnt(2)
	v_pk_mul_f32 v[10:11], v[170:171], v[156:157]
	v_pk_fma_f32 v[34:35], v[36:37], v[96:97], v[34:35] op_sel_hi:[1,0,1] neg_lo:[0,0,1] neg_hi:[0,0,1]
	v_pk_mul_f32 v[36:37], v[170:171], v[126:127]
	v_pk_fma_f32 v[98:99], v[12:13], v[96:97], v[10:11] op_sel_hi:[1,0,1] neg_lo:[0,0,1] neg_hi:[0,0,1]
	v_pk_fma_f32 v[56:57], v[38:39], v[96:97], v[36:37] op_sel_hi:[1,0,1] neg_lo:[0,0,1] neg_hi:[0,0,1]
	v_pk_mul_f32 v[36:37], v[170:171], v[128:129]
	v_pk_mul_f32 v[38:39], v[170:171], v[130:131]
	v_pk_fma_f32 v[36:37], v[40:41], v[96:97], v[36:37] op_sel_hi:[1,0,1] neg_lo:[0,0,1] neg_hi:[0,0,1]
	v_pk_fma_f32 v[58:59], v[42:43], v[96:97], v[38:39] op_sel_hi:[1,0,1] neg_lo:[0,0,1] neg_hi:[0,0,1]
	v_pk_mul_f32 v[38:39], v[170:171], v[132:133]
	v_pk_mul_f32 v[40:41], v[170:171], v[134:135]
	v_pk_fma_f32 v[38:39], v[44:45], v[96:97], v[38:39] op_sel_hi:[1,0,1] neg_lo:[0,0,1] neg_hi:[0,0,1]
	v_pk_fma_f32 v[44:45], v[46:47], v[96:97], v[40:41] op_sel_hi:[1,0,1] neg_lo:[0,0,1] neg_hi:[0,0,1]
	v_pk_mul_f32 v[40:41], v[170:171], v[136:137]
	v_pk_mul_f32 v[10:11], v[170:171], v[158:159]
	v_pk_fma_f32 v[16:17], v[16:17], v[96:97], v[40:41] op_sel_hi:[1,0,1] neg_lo:[0,0,1] neg_hi:[0,0,1]
	v_pk_mul_f32 v[40:41], v[170:171], v[138:139]
	v_pk_mul_f32 v[224:225], v[104:105], v[104:105]
	v_pk_fma_f32 v[40:41], v[18:19], v[96:97], v[40:41] op_sel_hi:[1,0,1] neg_lo:[0,0,1] neg_hi:[0,0,1]
	v_pk_mul_f32 v[18:19], v[170:171], v[140:141]
	v_pk_fma_f32 v[14:15], v[14:15], v[96:97], v[10:11] op_sel_hi:[1,0,1] neg_lo:[0,0,1] neg_hi:[0,0,1]
	v_pk_fma_f32 v[18:19], v[20:21], v[96:97], v[18:19] op_sel_hi:[1,0,1] neg_lo:[0,0,1] neg_hi:[0,0,1]
	v_pk_mul_f32 v[20:21], v[170:171], v[142:143]
	v_pk_mul_f32 v[226:227], v[106:107], v[106:107]
	v_pk_fma_f32 v[42:43], v[22:23], v[96:97], v[20:21] op_sel_hi:[1,0,1] neg_lo:[0,0,1] neg_hi:[0,0,1]
	v_pk_mul_f32 v[20:21], v[170:171], v[148:149]
	v_pk_mul_f32 v[22:23], v[170:171], v[150:151]
	v_pk_fma_f32 v[20:21], v[24:25], v[96:97], v[20:21] op_sel_hi:[1,0,1] neg_lo:[0,0,1] neg_hi:[0,0,1]
	v_pk_fma_f32 v[26:27], v[26:27], v[96:97], v[22:23] op_sel_hi:[1,0,1] neg_lo:[0,0,1] neg_hi:[0,0,1]
	v_pk_mul_f32 v[22:23], v[170:171], v[152:153]
	v_pk_mul_f32 v[24:25], v[170:171], v[154:155]
	v_pk_fma_f32 v[22:23], v[28:29], v[96:97], v[22:23] op_sel_hi:[1,0,1] neg_lo:[0,0,1] neg_hi:[0,0,1]
	v_pk_fma_f32 v[28:29], v[30:31], v[96:97], v[24:25] op_sel_hi:[1,0,1] neg_lo:[0,0,1] neg_hi:[0,0,1]
	s_waitcnt lgkmcnt(1)
	v_pk_mul_f32 v[24:25], v[170:171], v[216:217]
	v_pk_mul_f32 v[228:229], v[48:49], v[48:49]
	v_pk_fma_f32 v[0:1], v[0:1], v[96:97], v[24:25] op_sel_hi:[1,0,1] neg_lo:[0,0,1] neg_hi:[0,0,1]
	v_pk_mul_f32 v[24:25], v[170:171], v[218:219]
	v_pk_mul_f32 v[230:231], v[108:109], v[108:109]
	v_pk_fma_f32 v[24:25], v[2:3], v[96:97], v[24:25] op_sel_hi:[1,0,1] neg_lo:[0,0,1] neg_hi:[0,0,1]
	s_waitcnt lgkmcnt(0)
	v_pk_mul_f32 v[2:3], v[170:171], v[220:221]
	v_pk_mul_f32 v[112:113], v[50:51], v[50:51]
	v_pk_fma_f32 v[2:3], v[4:5], v[96:97], v[2:3] op_sel_hi:[1,0,1] neg_lo:[0,0,1] neg_hi:[0,0,1]
	v_pk_mul_f32 v[4:5], v[170:171], v[222:223]
	v_pk_mul_f32 v[114:115], v[110:111], v[110:111]
	v_pk_fma_f32 v[6:7], v[6:7], v[96:97], v[4:5] op_sel_hi:[1,0,1] neg_lo:[0,0,1] neg_hi:[0,0,1]
	v_pk_mul_f32 v[4:5], v[170:171], v[144:145]
	v_pk_mul_f32 v[116:117], v[52:53], v[52:53]
	v_pk_fma_f32 v[4:5], v[8:9], v[96:97], v[4:5] op_sel_hi:[1,0,1] neg_lo:[0,0,1] neg_hi:[0,0,1]
	v_add_f32_e32 v96, v224, v225
	v_add_f32_e32 v96, v226, v96
	v_add_f32_e32 v96, v227, v96
	v_add_f32_e32 v96, v228, v96
	v_add_f32_e32 v96, v229, v96
	v_add_f32_e32 v96, v230, v96
	v_add_f32_e32 v96, v231, v96
	v_add_f32_e32 v96, v112, v96
	v_add_f32_e32 v96, v113, v96
	v_add_f32_e32 v96, v114, v96
	v_add_f32_e32 v96, v115, v96
	v_add_f32_e32 v96, v116, v96
	v_pk_mul_f32 v[62:63], v[60:61], v[60:61]
	v_add_f32_e32 v96, v117, v96
	v_add_f32_e32 v62, v62, v96
	v_pk_mul_f32 v[118:119], v[32:33], v[32:33]
	v_add_f32_e32 v62, v63, v62
	v_add_f32_e32 v62, v118, v62
	v_pk_mul_f32 v[120:121], v[54:55], v[54:55]
	v_add_f32_e32 v62, v119, v62
	s_mov_b64 s[10:11], s[56:57]
	v_lshlrev_b32_e32 v10, 2, v172
	v_mov_b32_e32 v11, v161
	v_add_f32_e32 v62, v120, v62
	v_pk_mul_f32 v[122:123], v[34:35], v[34:35]
	v_lshl_add_u64 v[102:103], s[10:11], 0, v[10:11]
	v_add_f32_e32 v62, v121, v62
	flat_load_dwordx4 v[10:13], v[102:103]
	global_load_dwordx4 v[64:67], v[102:103], off offset:32
	global_load_dwordx4 v[68:71], v[102:103], off offset:64
	global_load_dwordx4 v[72:75], v[102:103], off offset:96
	global_load_dwordx4 v[76:79], v[102:103], off offset:128
	global_load_dwordx4 v[80:83], v[102:103], off offset:160
	global_load_dwordx4 v[84:87], v[102:103], off offset:192
	global_load_dwordx4 v[88:91], v[102:103], off offset:224
	global_load_dwordx4 v[92:95], v[102:103], off offset:256
	global_load_dwordx4 v[224:227], v[102:103], off offset:288
	global_load_dwordx4 v[228:231], v[102:103], off offset:320
	global_load_dwordx4 v[232:235], v[102:103], off offset:352
	global_load_dwordx4 v[236:239], v[102:103], off offset:384
	global_load_dwordx4 v[240:243], v[102:103], off offset:416
	global_load_dwordx4 v[244:247], v[102:103], off offset:448
	global_load_dwordx4 v[248:251], v[102:103], off offset:480
	v_add_f32_e32 v62, v122, v62
	v_pk_mul_f32 v[124:125], v[56:57], v[56:57]
	v_add_f32_e32 v62, v123, v62
	v_add_f32_e32 v62, v124, v62
	v_pk_mul_f32 v[126:127], v[36:37], v[36:37]
	v_add_f32_e32 v62, v125, v62
	v_add_f32_e32 v62, v126, v62
	v_pk_mul_f32 v[128:129], v[58:59], v[58:59]
	v_add_f32_e32 v62, v127, v62
	v_add_f32_e32 v62, v128, v62
	v_pk_mul_f32 v[130:131], v[38:39], v[38:39]
	v_add_f32_e32 v62, v129, v62
	v_add_f32_e32 v62, v130, v62
	v_pk_mul_f32 v[46:47], v[44:45], v[44:45]
	v_add_f32_e32 v62, v131, v62
	v_add_f32_e32 v46, v46, v62
	v_pk_mul_f32 v[132:133], v[16:17], v[16:17]
	v_add_f32_e32 v46, v47, v46
	v_add_f32_e32 v46, v132, v46
	v_pk_mul_f32 v[134:135], v[40:41], v[40:41]
	v_add_f32_e32 v46, v133, v46
	v_add_f32_e32 v46, v134, v46
	v_pk_mul_f32 v[136:137], v[18:19], v[18:19]
	v_add_f32_e32 v46, v135, v46
	v_add_f32_e32 v46, v136, v46
	v_pk_mul_f32 v[138:139], v[42:43], v[42:43]
	v_add_f32_e32 v46, v137, v46
	v_add_f32_e32 v46, v138, v46
	v_pk_mul_f32 v[140:141], v[20:21], v[20:21]
	v_add_f32_e32 v46, v139, v46
	v_add_f32_e32 v46, v140, v46
	v_pk_mul_f32 v[142:143], v[26:27], v[26:27]
	v_add_f32_e32 v46, v141, v46
	v_add_f32_e32 v46, v142, v46
	v_pk_mul_f32 v[148:149], v[22:23], v[22:23]
	v_add_f32_e32 v46, v143, v46
	v_add_f32_e32 v46, v148, v46
	v_pk_mul_f32 v[30:31], v[28:29], v[28:29]
	v_add_f32_e32 v46, v149, v46
	v_add_f32_e32 v30, v30, v46
	v_pk_mul_f32 v[150:151], v[0:1], v[0:1]
	v_add_f32_e32 v30, v31, v30
	v_add_f32_e32 v30, v150, v30
	v_pk_mul_f32 v[152:153], v[24:25], v[24:25]
	v_add_f32_e32 v30, v151, v30
	v_add_f32_e32 v30, v152, v30
	v_pk_mul_f32 v[154:155], v[2:3], v[2:3]
	v_add_f32_e32 v30, v153, v30
	v_add_f32_e32 v30, v154, v30
	v_pk_mul_f32 v[216:217], v[6:7], v[6:7]
	v_add_f32_e32 v30, v155, v30
	v_add_f32_e32 v30, v216, v30
	v_pk_mul_f32 v[8:9], v[4:5], v[4:5]
	v_add_f32_e32 v30, v217, v30
	v_add_f32_e32 v8, v8, v30
	v_pk_mul_f32 v[146:147], v[100:101], v[100:101]
	v_add_f32_e32 v8, v9, v8
	v_add_f32_e32 v8, v146, v8
	v_pk_mul_f32 v[156:157], v[98:99], v[98:99]
	v_add_f32_e32 v8, v147, v8
	v_add_f32_e32 v8, v156, v8
	v_pk_mul_f32 v[158:159], v[14:15], v[14:15]
	v_add_f32_e32 v8, v157, v8
	v_add_f32_e32 v8, v158, v8
	v_add_f32_e32 v8, v159, v8
	ds_bpermute_b32 v9, v181, v8
	s_waitcnt lgkmcnt(0)
	v_add_f32_e32 v8, v8, v9
	v_fmamk_f32 v8, v8, 0x3c000000, v182
	v_mul_f32_e32 v9, 0x4f800000, v8
	v_cmp_gt_f32_e32 vcc, s50, v8
	s_nop 1
	v_cndmask_b32_e32 v8, v8, v9, vcc
	v_sqrt_f32_e32 v9, v8
	s_nop 0
	v_add_u32_e32 v30, -1, v9
	v_fma_f32 v31, -v30, v9, v8
	v_cmp_ge_f32_e64 s[10:11], 0, v31
	v_add_u32_e32 v31, 1, v9
	s_nop 0
	v_cndmask_b32_e64 v30, v9, v30, s[10:11]
	v_fma_f32 v9, -v31, v9, v8
	v_cmp_lt_f32_e64 s[10:11], 0, v9
	s_nop 1
	v_cndmask_b32_e64 v9, v30, v31, s[10:11]
	v_mul_f32_e32 v30, 0x37800000, v9
	v_cndmask_b32_e32 v9, v9, v30, vcc
	v_cmp_class_f32_e32 vcc, v8, v183
	s_nop 1
	v_cndmask_b32_e32 v8, v9, v8, vcc
	v_div_scale_f32 v9, s[10:11], v8, v8, v200
	v_rcp_f32_e32 v30, v9
	s_nop 0
	v_fma_f32 v31, -v9, v30, 1.0
	v_fmac_f32_e32 v30, v31, v30
	v_div_scale_f32 v31, vcc, v200, v8, v200
	v_mul_f32_e32 v46, v31, v30
	v_fma_f32 v47, -v9, v46, v31
	v_fmac_f32_e32 v46, v47, v30
	v_fma_f32 v9, -v9, v46, v31
	v_div_fmas_f32 v9, v9, v30, v46
	v_div_fixup_f32 v30, v9, v8, v200
	v_pk_mul_f32 v[8:9], v[104:105], v[30:31] op_sel_hi:[1,0]
	v_pk_mul_f32 v[46:47], v[106:107], v[30:31] op_sel_hi:[1,0]
	s_waitcnt vmcnt(15)
	v_pk_mul_f32 v[10:11], v[10:11], v[8:9]
	v_pk_mul_f32 v[12:13], v[12:13], v[46:47]
	ds_write_b128 v215, v[10:13]
	s_nop 1
	v_pk_mul_f32 v[12:13], v[108:109], v[30:31] op_sel_hi:[1,0]
	v_pk_mul_f32 v[46:47], v[48:49], v[30:31] op_sel_hi:[1,0]
	v_pk_mul_f32 v[32:33], v[32:33], v[30:31] op_sel_hi:[1,0]
	v_pk_mul_f32 v[16:17], v[16:17], v[30:31] op_sel_hi:[1,0]
	v_pk_mul_f32 v[0:1], v[0:1], v[30:31] op_sel_hi:[1,0]
	v_pk_mul_f32 v[6:7], v[6:7], v[30:31] op_sel_hi:[1,0]
	v_pk_mul_f32 v[4:5], v[4:5], v[30:31] op_sel_hi:[1,0]
	s_waitcnt vmcnt(14)
	v_pk_mul_f32 v[8:9], v[64:65], v[46:47]
	v_pk_mul_f32 v[10:11], v[66:67], v[12:13]
	ds_write_b128 v215, v[8:11] offset:32
	s_nop 1
	v_pk_mul_f32 v[12:13], v[110:111], v[30:31] op_sel_hi:[1,0]
	v_pk_mul_f32 v[46:47], v[50:51], v[30:31] op_sel_hi:[1,0]
	s_waitcnt vmcnt(13)
	v_pk_mul_f32 v[10:11], v[70:71], v[12:13]
	v_pk_mul_f32 v[8:9], v[68:69], v[46:47]
	ds_write_b128 v215, v[8:11] offset:64
	s_nop 1
	v_pk_mul_f32 v[12:13], v[60:61], v[30:31] op_sel_hi:[1,0]
	v_pk_mul_f32 v[46:47], v[52:53], v[30:31] op_sel_hi:[1,0]
	s_waitcnt vmcnt(12)
	v_pk_mul_f32 v[10:11], v[74:75], v[12:13]
	v_pk_mul_f32 v[8:9], v[72:73], v[46:47]
	ds_write_b128 v215, v[8:11] offset:96
	s_nop 1
	v_pk_mul_f32 v[12:13], v[54:55], v[30:31] op_sel_hi:[1,0]
	s_waitcnt vmcnt(11)
	v_pk_mul_f32 v[8:9], v[76:77], v[32:33]
	v_pk_mul_f32 v[10:11], v[78:79], v[12:13]
	ds_write_b128 v215, v[8:11] offset:128
	s_nop 1
	v_pk_mul_f32 v[12:13], v[56:57], v[30:31] op_sel_hi:[1,0]
	v_pk_mul_f32 v[32:33], v[34:35], v[30:31] op_sel_hi:[1,0]
	s_waitcnt vmcnt(10)
	v_pk_mul_f32 v[10:11], v[82:83], v[12:13]
	v_pk_mul_f32 v[8:9], v[80:81], v[32:33]
	ds_write_b128 v215, v[8:11] offset:160
	s_nop 1
	v_pk_mul_f32 v[12:13], v[58:59], v[30:31] op_sel_hi:[1,0]
	v_pk_mul_f32 v[32:33], v[36:37], v[30:31] op_sel_hi:[1,0]
	s_waitcnt vmcnt(9)
	v_pk_mul_f32 v[10:11], v[86:87], v[12:13]
	v_pk_mul_f32 v[8:9], v[84:85], v[32:33]
	ds_write_b128 v215, v[8:11] offset:192
	s_nop 1
	v_pk_mul_f32 v[12:13], v[44:45], v[30:31] op_sel_hi:[1,0]
	v_pk_mul_f32 v[32:33], v[38:39], v[30:31] op_sel_hi:[1,0]
	s_waitcnt vmcnt(8)
	v_pk_mul_f32 v[10:11], v[90:91], v[12:13]
	v_pk_mul_f32 v[8:9], v[88:89], v[32:33]
	ds_write_b128 v215, v[8:11] offset:224
	s_nop 1
	v_pk_mul_f32 v[12:13], v[40:41], v[30:31] op_sel_hi:[1,0]
	s_waitcnt vmcnt(7)
	v_pk_mul_f32 v[8:9], v[92:93], v[16:17]
	v_pk_mul_f32 v[10:11], v[94:95], v[12:13]
	ds_write_b128 v215, v[8:11] offset:256
	s_nop 1
	v_pk_mul_f32 v[12:13], v[42:43], v[30:31] op_sel_hi:[1,0]
	v_pk_mul_f32 v[16:17], v[18:19], v[30:31] op_sel_hi:[1,0]
	s_waitcnt vmcnt(6)
	v_pk_mul_f32 v[10:11], v[226:227], v[12:13]
	v_pk_mul_f32 v[8:9], v[224:225], v[16:17]
	ds_write_b128 v215, v[8:11] offset:288
	s_nop 1
	v_pk_mul_f32 v[12:13], v[26:27], v[30:31] op_sel_hi:[1,0]
	v_pk_mul_f32 v[16:17], v[20:21], v[30:31] op_sel_hi:[1,0]
	s_waitcnt vmcnt(5)
	v_pk_mul_f32 v[10:11], v[230:231], v[12:13]
	v_pk_mul_f32 v[8:9], v[228:229], v[16:17]
	ds_write_b128 v215, v[8:11] offset:320
	s_nop 1
	v_pk_mul_f32 v[12:13], v[28:29], v[30:31] op_sel_hi:[1,0]
	v_pk_mul_f32 v[16:17], v[22:23], v[30:31] op_sel_hi:[1,0]
	s_waitcnt vmcnt(4)
	v_pk_mul_f32 v[10:11], v[234:235], v[12:13]
	v_pk_mul_f32 v[8:9], v[232:233], v[16:17]
	ds_write_b128 v215, v[8:11] offset:352
	s_nop 1
	v_pk_mul_f32 v[12:13], v[24:25], v[30:31] op_sel_hi:[1,0]
	s_waitcnt vmcnt(3)
	v_pk_mul_f32 v[8:9], v[236:237], v[0:1]
	v_pk_mul_f32 v[10:11], v[238:239], v[12:13]
	ds_write_b128 v215, v[8:11] offset:384
	s_nop 1
	v_pk_mul_f32 v[0:1], v[2:3], v[30:31] op_sel_hi:[1,0]
	s_waitcnt vmcnt(2)
	v_pk_mul_f32 v[2:3], v[242:243], v[6:7]
	v_pk_mul_f32 v[0:1], v[240:241], v[0:1]
	ds_write_b128 v215, v[0:3] offset:416
	s_nop 1
	v_pk_mul_f32 v[6:7], v[100:101], v[30:31] op_sel_hi:[1,0]
	s_waitcnt vmcnt(1)
	v_pk_mul_f32 v[0:1], v[244:245], v[4:5]
	v_pk_mul_f32 v[2:3], v[246:247], v[6:7]
	ds_write_b128 v215, v[0:3] offset:448
	s_nop 1
	v_pk_mul_f32 v[4:5], v[14:15], v[30:31] op_sel_hi:[1,0]
	v_pk_mul_f32 v[6:7], v[98:99], v[30:31] op_sel_hi:[1,0]
	s_waitcnt vmcnt(0)
	v_pk_mul_f32 v[2:3], v[250:251], v[4:5]
	v_pk_mul_f32 v[0:1], v[248:249], v[6:7]
	ds_write_b128 v215, v[0:3] offset:480
	s_branch .LBB0_400
